# hand-scheduled software-pipelined unmasked attention main loop (K/V fragment prefetch one unit ahead, permlane32 cross-half max, SGPR-static ring addressing, x3 unroll) + rest-tail conversion
# speedup vs baseline: 1.0253x; 1.0231x over previous
.Lam_entry:
	v_and_b32_e32 v152, 31, v203
	v_lshlrev_b32_e32 v152, 8, v152
	v_lshrrev_b32_e32 v153, 5, v203
	v_and_b32_e32 v48, 15, v203
	v_xor_b32_e32 v48, v48, v153
	v_xor_b32_e32 v242, 0, v48
	v_lshl_add_u32 v242, v242, 4, v152
	v_xor_b32_e32 v243, 2, v48
	v_lshl_add_u32 v243, v243, 4, v152
	v_xor_b32_e32 v244, 4, v48
	v_lshl_add_u32 v244, v244, 4, v152
	v_xor_b32_e32 v245, 6, v48
	v_lshl_add_u32 v245, v245, 4, v152
	v_xor_b32_e32 v246, 8, v48
	v_lshl_add_u32 v246, v246, 4, v152
	v_xor_b32_e32 v247, 10, v48
	v_lshl_add_u32 v247, v247, 4, v152
	v_xor_b32_e32 v248, 12, v48
	v_lshl_add_u32 v248, v248, 4, v152
	v_xor_b32_e32 v249, 14, v48
	v_lshl_add_u32 v249, v249, 4, v152
	v_mov_b32_e32 v94, v242
	v_mov_b32_e32 v95, v243
	v_mov_b32_e32 v97, v244
	v_mov_b32_e32 v147, v245
	v_mov_b32_e32 v200, v246
	v_mov_b32_e32 v201, v247
	s_mov_b32 s81, s80
	s_lshl_b32 s82, s48, 11
	s_lshl_b32 s83, s48, 10
	s_mov_b64 s[84:85], s[20:21]
	s_mov_b64 s[88:89], s[18:19]
	s_mov_b64 s[86:87], s[38:39]
	s_mov_b64 s[90:91], s[44:45]
	s_mov_b32 s92, 0
	ds_read_b128 v[218:221], v94 offset:8192
	ds_read_b128 v[222:225], v95 offset:8192
	ds_read_b128 v[226:229], v97 offset:8192
	ds_read_b128 v[230:233], v147 offset:8192
	ds_read_b128 v[234:237], v200 offset:8192
	ds_read_b128 v[238:241], v201 offset:8192
.Lam_loop:
	s_waitcnt vmcnt(3)
	s_barrier
	s_add_u32 m0, s82, 0x18000
	v_lshl_add_u64 v[152:153], v[142:143], 0, s[84:85]
	global_load_lds_dwordx4 v[152:153], off
	s_add_u32 m0, s82, 0x18400
	v_lshl_add_u64 v[152:153], v[144:145], 0, s[84:85]
	global_load_lds_dwordx4 v[152:153], off
	s_add_u32 m0, s83, 0x1c000
	v_lshl_add_u64 v[152:153], v[140:141], 0, s[86:87]
	global_load_lds_dwordx4 v[152:153], off
	s_add_u32 m0, s82, 0x1e000
	v_lshl_add_u64 v[152:153], v[142:143], 0, s[88:89]
	global_load_lds_dwordx4 v[152:153], off
	s_add_u32 m0, s82, 0x1e400
	v_lshl_add_u64 v[152:153], v[144:145], 0, s[88:89]
	global_load_lds_dwordx4 v[152:153], off
	s_add_u32 m0, s83, 0x22000
	v_lshl_add_u64 v[152:153], v[140:141], 0, s[90:91]
	global_load_lds_dwordx4 v[152:153], off
	s_add_u32 s84, s84, 0x30000
	s_addc_u32 s85, s85, 0
	s_add_u32 s88, s88, 0x30000
	s_addc_u32 s89, s89, 0
	s_add_u32 s86, s86, 0x100
	s_addc_u32 s87, s87, 0
	s_add_u32 s90, s90, 0x100
	s_addc_u32 s91, s91, 0
	s_cmp_eq_u32 s92, 0
	s_cselect_b32 s93, 0, 0xfffe8000
	s_mov_b32 s92, 1
	v_add_u32_e32 v242, s93, v242
	v_add_u32_e32 v243, s93, v243
	v_add_u32_e32 v244, s93, v244
	v_add_u32_e32 v245, s93, v245
	v_add_u32_e32 v246, s93, v246
	v_add_u32_e32 v247, s93, v247
	v_add_u32_e32 v248, s93, v248
	v_add_u32_e32 v249, s93, v249
	ds_read_b128 v[90:93], v243 offset:16384
	ds_read_b128 v[148:151], v247 offset:16384
	s_waitcnt lgkmcnt(7)
	v_mfma_f32_32x32x16_bf16 v[48:63], v[218:221], v[66:69], 0
	ds_read_b128 v[218:221], v94 offset:24576
	v_max3_f32 v152, v32, v33, v34
	v_max3_f32 v152, v152, v35, v36
	v_max3_f32 v152, v152, v37, v38
	v_max3_f32 v152, v152, v39, v40
	v_max3_f32 v152, v152, v41, v42
	v_max3_f32 v152, v152, v43, v44
	v_max3_f32 v152, v152, v45, v46
	v_max_f32_e32 v152, v152, v47
	s_waitcnt lgkmcnt(7)
	v_mfma_f32_32x32x16_bf16 v[48:63], v[222:225], v[70:73], v[48:63]
	ds_read_b128 v[222:225], v95 offset:24576
	v_mov_b32_e32 v153, v152
	s_nop 1
	v_permlane32_swap_b32_e32 v153, v152
	v_max_f32_e32 v152, v152, v153
	v_add_f32_e32 v153, 0x41000000, v217
	v_cmp_lt_f32_e32 vcc, v153, v152
	s_cbranch_vccnz .Lam_c0u0_rare
.Lam_c0u0_back:
	v_sub_f32_e32 v32, v32, v217
	v_exp_f32_e32 v32, v32
	v_sub_f32_e32 v33, v33, v217
	v_exp_f32_e32 v33, v33
	s_waitcnt lgkmcnt(7)
	v_mfma_f32_32x32x16_bf16 v[48:63], v[226:229], v[74:77], v[48:63]
	ds_read_b128 v[226:229], v97 offset:24576
	v_sub_f32_e32 v34, v34, v217
	v_exp_f32_e32 v34, v34
	v_sub_f32_e32 v35, v35, v217
	v_exp_f32_e32 v35, v35
	v_sub_f32_e32 v36, v36, v217
	v_exp_f32_e32 v36, v36
	v_sub_f32_e32 v37, v37, v217
	s_waitcnt lgkmcnt(7)
	v_mfma_f32_32x32x16_bf16 v[48:63], v[230:233], v[78:81], v[48:63]
	ds_read_b128 v[230:233], v147 offset:24576
	v_exp_f32_e32 v37, v37
	v_sub_f32_e32 v38, v38, v217
	v_exp_f32_e32 v38, v38
	v_sub_f32_e32 v39, v39, v217
	v_exp_f32_e32 v39, v39
	v_add_f32_e32 v153, v32, v33
	v_add_f32_e32 v153, v153, v34
	s_waitcnt lgkmcnt(7)
	v_mfma_f32_32x32x16_bf16 v[48:63], v[234:237], v[82:85], v[48:63]
	ds_read_b128 v[234:237], v242 offset:16384
	v_add_f32_e32 v153, v153, v35
	v_add_f32_e32 v153, v153, v36
	v_add_f32_e32 v153, v153, v37
	v_add_f32_e32 v153, v153, v38
	v_add_f32_e32 v153, v153, v39
	v_cvt_pk_bf16_f32 v32, v32, v33
	v_cvt_pk_bf16_f32 v33, v34, v35
	s_waitcnt lgkmcnt(7)
	v_mfma_f32_32x32x16_bf16 v[48:63], v[238:241], v[86:89], v[48:63]
	ds_read_b128 v[238:241], v246 offset:16384
	v_cvt_pk_bf16_f32 v34, v36, v37
	v_cvt_pk_bf16_f32 v35, v38, v39
	s_nop 1
	s_waitcnt lgkmcnt(1)
	v_mfma_f32_32x32x16_bf16 v[0:15], v[234:237], v[32:35], v[0:15]
	ds_read_b128 v[234:237], v200 offset:24576
	v_sub_f32_e32 v40, v40, v217
	v_exp_f32_e32 v40, v40
	v_sub_f32_e32 v41, v41, v217
	v_exp_f32_e32 v41, v41
	v_sub_f32_e32 v42, v42, v217
	v_exp_f32_e32 v42, v42
	v_sub_f32_e32 v43, v43, v217
	v_exp_f32_e32 v43, v43
	s_waitcnt lgkmcnt(1)
	v_mfma_f32_32x32x16_bf16 v[16:31], v[238:241], v[32:35], v[16:31]
	ds_read_b128 v[238:241], v201 offset:24576
	v_sub_f32_e32 v44, v44, v217
	v_exp_f32_e32 v44, v44
	v_sub_f32_e32 v45, v45, v217
	v_exp_f32_e32 v45, v45
	v_sub_f32_e32 v46, v46, v217
	v_exp_f32_e32 v46, v46
	v_sub_f32_e32 v47, v47, v217
	v_exp_f32_e32 v47, v47
	v_add_f32_e32 v153, v153, v40
	v_add_f32_e32 v153, v153, v41
	v_add_f32_e32 v153, v153, v42
	v_add_f32_e32 v153, v153, v43
	v_add_f32_e32 v153, v153, v44
	v_add_f32_e32 v153, v153, v45
	v_add_f32_e32 v153, v153, v46
	v_add_f32_e32 v153, v153, v47
	v_cvt_pk_bf16_f32 v40, v40, v41
	v_cvt_pk_bf16_f32 v41, v42, v43
	v_cvt_pk_bf16_f32 v42, v44, v45
	v_cvt_pk_bf16_f32 v43, v46, v47
	v_add_f32_e32 v96, v96, v153
	s_nop 0
	v_mfma_f32_32x32x16_bf16 v[0:15], v[90:93], v[40:43], v[0:15]
	v_mfma_f32_32x32x16_bf16 v[16:31], v[148:151], v[40:43], v[16:31]
	ds_read_b128 v[90:93], v245 offset:16384
	ds_read_b128 v[148:151], v249 offset:16384
	v_mfma_f32_32x32x16_bf16 v[32:47], v[218:221], v[66:69], 0
	ds_read_b128 v[218:221], v94 offset:32768
	v_max3_f32 v152, v48, v49, v50
	v_max3_f32 v152, v152, v51, v52
	v_max3_f32 v152, v152, v53, v54
	v_max3_f32 v152, v152, v55, v56
	v_max3_f32 v152, v152, v57, v58
	v_max3_f32 v152, v152, v59, v60
	v_max3_f32 v152, v152, v61, v62
	v_max_f32_e32 v152, v152, v63
	v_mfma_f32_32x32x16_bf16 v[32:47], v[222:225], v[70:73], v[32:47]
	ds_read_b128 v[222:225], v95 offset:32768
	v_mov_b32_e32 v153, v152
	s_nop 1
	v_permlane32_swap_b32_e32 v153, v152
	v_max_f32_e32 v152, v152, v153
	v_add_f32_e32 v153, 0x41000000, v217
	v_cmp_lt_f32_e32 vcc, v153, v152
	s_cbranch_vccnz .Lam_c0u1_rare
.Lam_c0u1_back:
	v_sub_f32_e32 v48, v48, v217
	v_exp_f32_e32 v48, v48
	v_sub_f32_e32 v49, v49, v217
	v_exp_f32_e32 v49, v49
	v_mfma_f32_32x32x16_bf16 v[32:47], v[226:229], v[74:77], v[32:47]
	ds_read_b128 v[226:229], v97 offset:32768
	v_sub_f32_e32 v50, v50, v217
	v_exp_f32_e32 v50, v50
	v_sub_f32_e32 v51, v51, v217
	v_exp_f32_e32 v51, v51
	v_sub_f32_e32 v52, v52, v217
	v_exp_f32_e32 v52, v52
	v_sub_f32_e32 v53, v53, v217
	v_mfma_f32_32x32x16_bf16 v[32:47], v[230:233], v[78:81], v[32:47]
	ds_read_b128 v[230:233], v147 offset:32768
	v_exp_f32_e32 v53, v53
	v_sub_f32_e32 v54, v54, v217
	v_exp_f32_e32 v54, v54
	v_sub_f32_e32 v55, v55, v217
	v_exp_f32_e32 v55, v55
	v_add_f32_e32 v153, v48, v49
	v_add_f32_e32 v153, v153, v50
	s_waitcnt lgkmcnt(7)
	v_mfma_f32_32x32x16_bf16 v[32:47], v[234:237], v[82:85], v[32:47]
	ds_read_b128 v[234:237], v244 offset:16384
	v_add_f32_e32 v153, v153, v51
	v_add_f32_e32 v153, v153, v52
	v_add_f32_e32 v153, v153, v53
	v_add_f32_e32 v153, v153, v54
	v_add_f32_e32 v153, v153, v55
	v_cvt_pk_bf16_f32 v48, v48, v49
	v_cvt_pk_bf16_f32 v49, v50, v51
	s_waitcnt lgkmcnt(7)
	v_mfma_f32_32x32x16_bf16 v[32:47], v[238:241], v[86:89], v[32:47]
	ds_read_b128 v[238:241], v248 offset:16384
	v_cvt_pk_bf16_f32 v50, v52, v53
	v_cvt_pk_bf16_f32 v51, v54, v55
	s_nop 1
	s_waitcnt lgkmcnt(1)
	v_mfma_f32_32x32x16_bf16 v[0:15], v[234:237], v[48:51], v[0:15]
	ds_read_b128 v[234:237], v200 offset:32768
	v_sub_f32_e32 v56, v56, v217
	v_exp_f32_e32 v56, v56
	v_sub_f32_e32 v57, v57, v217
	v_exp_f32_e32 v57, v57
	v_sub_f32_e32 v58, v58, v217
	v_exp_f32_e32 v58, v58
	v_sub_f32_e32 v59, v59, v217
	v_exp_f32_e32 v59, v59
	s_waitcnt lgkmcnt(1)
	v_mfma_f32_32x32x16_bf16 v[16:31], v[238:241], v[48:51], v[16:31]
	ds_read_b128 v[238:241], v201 offset:32768
	v_sub_f32_e32 v60, v60, v217
	v_exp_f32_e32 v60, v60
	v_sub_f32_e32 v61, v61, v217
	v_exp_f32_e32 v61, v61
	v_sub_f32_e32 v62, v62, v217
	v_exp_f32_e32 v62, v62
	v_sub_f32_e32 v63, v63, v217
	v_exp_f32_e32 v63, v63
	v_add_f32_e32 v153, v153, v56
	v_add_f32_e32 v153, v153, v57
	v_add_f32_e32 v153, v153, v58
	v_add_f32_e32 v153, v153, v59
	v_add_f32_e32 v153, v153, v60
	v_add_f32_e32 v153, v153, v61
	v_add_f32_e32 v153, v153, v62
	v_add_f32_e32 v153, v153, v63
	v_cvt_pk_bf16_f32 v56, v56, v57
	v_cvt_pk_bf16_f32 v57, v58, v59
	v_cvt_pk_bf16_f32 v58, v60, v61
	v_cvt_pk_bf16_f32 v59, v62, v63
	v_add_f32_e32 v96, v96, v153
	s_nop 0
	v_mfma_f32_32x32x16_bf16 v[0:15], v[90:93], v[56:59], v[0:15]
	v_mfma_f32_32x32x16_bf16 v[16:31], v[148:151], v[56:59], v[16:31]
	v_add_u32_e32 v94, 0xc000, v94
	v_add_u32_e32 v95, 0xc000, v95
	v_add_u32_e32 v97, 0xc000, v97
	v_add_u32_e32 v147, 0xc000, v147
	v_add_u32_e32 v200, 0xc000, v200
	v_add_u32_e32 v201, 0xc000, v201
	ds_read_b128 v[90:93], v243 offset:40960
	ds_read_b128 v[148:151], v247 offset:40960
	v_mfma_f32_32x32x16_bf16 v[48:63], v[218:221], v[66:69], 0
	ds_read_b128 v[218:221], v94
	v_max3_f32 v152, v32, v33, v34
	v_max3_f32 v152, v152, v35, v36
	v_max3_f32 v152, v152, v37, v38
	v_max3_f32 v152, v152, v39, v40
	v_max3_f32 v152, v152, v41, v42
	v_max3_f32 v152, v152, v43, v44
	v_max3_f32 v152, v152, v45, v46
	v_max_f32_e32 v152, v152, v47
	v_mfma_f32_32x32x16_bf16 v[48:63], v[222:225], v[70:73], v[48:63]
	ds_read_b128 v[222:225], v95
	v_mov_b32_e32 v153, v152
	s_nop 1
	v_permlane32_swap_b32_e32 v153, v152
	v_max_f32_e32 v152, v152, v153
	v_add_f32_e32 v153, 0x41000000, v217
	v_cmp_lt_f32_e32 vcc, v153, v152
	s_cbranch_vccnz .Lam_c0u2_rare
.Lam_c0u2_back:
	v_sub_f32_e32 v32, v32, v217
	v_exp_f32_e32 v32, v32
	v_sub_f32_e32 v33, v33, v217
	v_exp_f32_e32 v33, v33
	v_mfma_f32_32x32x16_bf16 v[48:63], v[226:229], v[74:77], v[48:63]
	ds_read_b128 v[226:229], v97
	v_sub_f32_e32 v34, v34, v217
	v_exp_f32_e32 v34, v34
	v_sub_f32_e32 v35, v35, v217
	v_exp_f32_e32 v35, v35
	v_sub_f32_e32 v36, v36, v217
	v_exp_f32_e32 v36, v36
	v_sub_f32_e32 v37, v37, v217
	v_mfma_f32_32x32x16_bf16 v[48:63], v[230:233], v[78:81], v[48:63]
	ds_read_b128 v[230:233], v147
	v_exp_f32_e32 v37, v37
	v_sub_f32_e32 v38, v38, v217
	v_exp_f32_e32 v38, v38
	v_sub_f32_e32 v39, v39, v217
	v_exp_f32_e32 v39, v39
	v_add_f32_e32 v153, v32, v33
	v_add_f32_e32 v153, v153, v34
	s_waitcnt lgkmcnt(7)
	v_mfma_f32_32x32x16_bf16 v[48:63], v[234:237], v[82:85], v[48:63]
	ds_read_b128 v[234:237], v242 offset:40960
	v_add_f32_e32 v153, v153, v35
	v_add_f32_e32 v153, v153, v36
	v_add_f32_e32 v153, v153, v37
	v_add_f32_e32 v153, v153, v38
	v_add_f32_e32 v153, v153, v39
	v_cvt_pk_bf16_f32 v32, v32, v33
	v_cvt_pk_bf16_f32 v33, v34, v35
	s_waitcnt lgkmcnt(7)
	v_mfma_f32_32x32x16_bf16 v[48:63], v[238:241], v[86:89], v[48:63]
	ds_read_b128 v[238:241], v246 offset:40960
	v_cvt_pk_bf16_f32 v34, v36, v37
	v_cvt_pk_bf16_f32 v35, v38, v39
	s_nop 1
	s_waitcnt lgkmcnt(1)
	v_mfma_f32_32x32x16_bf16 v[0:15], v[234:237], v[32:35], v[0:15]
	ds_read_b128 v[234:237], v200
	v_sub_f32_e32 v40, v40, v217
	v_exp_f32_e32 v40, v40
	v_sub_f32_e32 v41, v41, v217
	v_exp_f32_e32 v41, v41
	v_sub_f32_e32 v42, v42, v217
	v_exp_f32_e32 v42, v42
	v_sub_f32_e32 v43, v43, v217
	v_exp_f32_e32 v43, v43
	s_waitcnt lgkmcnt(1)
	v_mfma_f32_32x32x16_bf16 v[16:31], v[238:241], v[32:35], v[16:31]
	ds_read_b128 v[238:241], v201
	v_sub_f32_e32 v44, v44, v217
	v_exp_f32_e32 v44, v44
	v_sub_f32_e32 v45, v45, v217
	v_exp_f32_e32 v45, v45
	v_sub_f32_e32 v46, v46, v217
	v_exp_f32_e32 v46, v46
	v_sub_f32_e32 v47, v47, v217
	v_exp_f32_e32 v47, v47
	v_add_f32_e32 v153, v153, v40
	v_add_f32_e32 v153, v153, v41
	v_add_f32_e32 v153, v153, v42
	v_add_f32_e32 v153, v153, v43
	v_add_f32_e32 v153, v153, v44
	v_add_f32_e32 v153, v153, v45
	v_add_f32_e32 v153, v153, v46
	v_add_f32_e32 v153, v153, v47
	v_cvt_pk_bf16_f32 v40, v40, v41
	v_cvt_pk_bf16_f32 v41, v42, v43
	v_cvt_pk_bf16_f32 v42, v44, v45
	v_cvt_pk_bf16_f32 v43, v46, v47
	v_add_f32_e32 v96, v96, v153
	s_nop 0
	v_mfma_f32_32x32x16_bf16 v[0:15], v[90:93], v[40:43], v[0:15]
	v_mfma_f32_32x32x16_bf16 v[16:31], v[148:151], v[40:43], v[16:31]
	ds_read_b128 v[90:93], v245 offset:40960
	ds_read_b128 v[148:151], v249 offset:40960
	v_mfma_f32_32x32x16_bf16 v[32:47], v[218:221], v[66:69], 0
	ds_read_b128 v[218:221], v94 offset:8192
	v_max3_f32 v152, v48, v49, v50
	v_max3_f32 v152, v152, v51, v52
	v_max3_f32 v152, v152, v53, v54
	v_max3_f32 v152, v152, v55, v56
	v_max3_f32 v152, v152, v57, v58
	v_max3_f32 v152, v152, v59, v60
	v_max3_f32 v152, v152, v61, v62
	v_max_f32_e32 v152, v152, v63
	v_mfma_f32_32x32x16_bf16 v[32:47], v[222:225], v[70:73], v[32:47]
	ds_read_b128 v[222:225], v95 offset:8192
	v_mov_b32_e32 v153, v152
	s_nop 1
	v_permlane32_swap_b32_e32 v153, v152
	v_max_f32_e32 v152, v152, v153
	v_add_f32_e32 v153, 0x41000000, v217
	v_cmp_lt_f32_e32 vcc, v153, v152
	s_cbranch_vccnz .Lam_c0u3_rare
.Lam_c0u3_back:
	v_sub_f32_e32 v48, v48, v217
	v_exp_f32_e32 v48, v48
	v_sub_f32_e32 v49, v49, v217
	v_exp_f32_e32 v49, v49
	v_mfma_f32_32x32x16_bf16 v[32:47], v[226:229], v[74:77], v[32:47]
	ds_read_b128 v[226:229], v97 offset:8192
	v_sub_f32_e32 v50, v50, v217
	v_exp_f32_e32 v50, v50
	v_sub_f32_e32 v51, v51, v217
	v_exp_f32_e32 v51, v51
	v_sub_f32_e32 v52, v52, v217
	v_exp_f32_e32 v52, v52
	v_sub_f32_e32 v53, v53, v217
	v_mfma_f32_32x32x16_bf16 v[32:47], v[230:233], v[78:81], v[32:47]
	ds_read_b128 v[230:233], v147 offset:8192
	v_exp_f32_e32 v53, v53
	v_sub_f32_e32 v54, v54, v217
	v_exp_f32_e32 v54, v54
	v_sub_f32_e32 v55, v55, v217
	v_exp_f32_e32 v55, v55
	v_add_f32_e32 v153, v48, v49
	v_add_f32_e32 v153, v153, v50
	s_waitcnt lgkmcnt(7)
	v_mfma_f32_32x32x16_bf16 v[32:47], v[234:237], v[82:85], v[32:47]
	ds_read_b128 v[234:237], v244 offset:40960
	v_add_f32_e32 v153, v153, v51
	v_add_f32_e32 v153, v153, v52
	v_add_f32_e32 v153, v153, v53
	v_add_f32_e32 v153, v153, v54
	v_add_f32_e32 v153, v153, v55
	v_cvt_pk_bf16_f32 v48, v48, v49
	v_cvt_pk_bf16_f32 v49, v50, v51
	s_waitcnt lgkmcnt(7)
	v_mfma_f32_32x32x16_bf16 v[32:47], v[238:241], v[86:89], v[32:47]
	ds_read_b128 v[238:241], v248 offset:40960
	v_cvt_pk_bf16_f32 v50, v52, v53
	v_cvt_pk_bf16_f32 v51, v54, v55
	s_nop 1
	s_waitcnt lgkmcnt(1)
	v_mfma_f32_32x32x16_bf16 v[0:15], v[234:237], v[48:51], v[0:15]
	ds_read_b128 v[234:237], v200 offset:8192
	v_sub_f32_e32 v56, v56, v217
	v_exp_f32_e32 v56, v56
	v_sub_f32_e32 v57, v57, v217
	v_exp_f32_e32 v57, v57
	v_sub_f32_e32 v58, v58, v217
	v_exp_f32_e32 v58, v58
	v_sub_f32_e32 v59, v59, v217
	v_exp_f32_e32 v59, v59
	s_waitcnt lgkmcnt(1)
	v_mfma_f32_32x32x16_bf16 v[16:31], v[238:241], v[48:51], v[16:31]
	ds_read_b128 v[238:241], v201 offset:8192
	v_sub_f32_e32 v60, v60, v217
	v_exp_f32_e32 v60, v60
	v_sub_f32_e32 v61, v61, v217
	v_exp_f32_e32 v61, v61
	v_sub_f32_e32 v62, v62, v217
	v_exp_f32_e32 v62, v62
	v_sub_f32_e32 v63, v63, v217
	v_exp_f32_e32 v63, v63
	v_add_f32_e32 v153, v153, v56
	v_add_f32_e32 v153, v153, v57
	v_add_f32_e32 v153, v153, v58
	v_add_f32_e32 v153, v153, v59
	v_add_f32_e32 v153, v153, v60
	v_add_f32_e32 v153, v153, v61
	v_add_f32_e32 v153, v153, v62
	v_add_f32_e32 v153, v153, v63
	v_cvt_pk_bf16_f32 v56, v56, v57
	v_cvt_pk_bf16_f32 v57, v58, v59
	v_cvt_pk_bf16_f32 v58, v60, v61
	v_cvt_pk_bf16_f32 v59, v62, v63
	v_add_f32_e32 v96, v96, v153
	s_nop 0
	v_mfma_f32_32x32x16_bf16 v[0:15], v[90:93], v[56:59], v[0:15]
	v_mfma_f32_32x32x16_bf16 v[16:31], v[148:151], v[56:59], v[16:31]
	s_add_i32 s81, s81, -1
	s_cmp_eq_u32 s81, 0
	s_cbranch_scc1 .Lam_exit
	s_waitcnt vmcnt(3)
	s_barrier
	s_add_u32 m0, s82, 0x0
	v_lshl_add_u64 v[152:153], v[142:143], 0, s[84:85]
	global_load_lds_dwordx4 v[152:153], off
	s_add_u32 m0, s82, 0x400
	v_lshl_add_u64 v[152:153], v[144:145], 0, s[84:85]
	global_load_lds_dwordx4 v[152:153], off
	s_add_u32 m0, s83, 0x4000
	v_lshl_add_u64 v[152:153], v[140:141], 0, s[86:87]
	global_load_lds_dwordx4 v[152:153], off
	s_add_u32 m0, s82, 0x6000
	v_lshl_add_u64 v[152:153], v[142:143], 0, s[88:89]
	global_load_lds_dwordx4 v[152:153], off
	s_add_u32 m0, s82, 0x6400
	v_lshl_add_u64 v[152:153], v[144:145], 0, s[88:89]
	global_load_lds_dwordx4 v[152:153], off
	s_add_u32 m0, s83, 0xa000
	v_lshl_add_u64 v[152:153], v[140:141], 0, s[90:91]
	global_load_lds_dwordx4 v[152:153], off
	s_add_u32 s84, s84, 0x30000
	s_addc_u32 s85, s85, 0
	s_add_u32 s88, s88, 0x30000
	s_addc_u32 s89, s89, 0
	s_add_u32 s86, s86, 0x100
	s_addc_u32 s87, s87, 0
	s_add_u32 s90, s90, 0x100
	s_addc_u32 s91, s91, 0
	v_add_u32_e32 v242, 0xc000, v242
	v_add_u32_e32 v243, 0xc000, v243
	v_add_u32_e32 v244, 0xc000, v244
	v_add_u32_e32 v245, 0xc000, v245
	v_add_u32_e32 v246, 0xc000, v246
	v_add_u32_e32 v247, 0xc000, v247
	v_add_u32_e32 v248, 0xc000, v248
	v_add_u32_e32 v249, 0xc000, v249
	ds_read_b128 v[90:93], v243 offset:16384
	ds_read_b128 v[148:151], v247 offset:16384
	v_mfma_f32_32x32x16_bf16 v[48:63], v[218:221], v[66:69], 0
	ds_read_b128 v[218:221], v94 offset:24576
	v_max3_f32 v152, v32, v33, v34
	v_max3_f32 v152, v152, v35, v36
	v_max3_f32 v152, v152, v37, v38
	v_max3_f32 v152, v152, v39, v40
	v_max3_f32 v152, v152, v41, v42
	v_max3_f32 v152, v152, v43, v44
	v_max3_f32 v152, v152, v45, v46
	v_max_f32_e32 v152, v152, v47
	v_mfma_f32_32x32x16_bf16 v[48:63], v[222:225], v[70:73], v[48:63]
	ds_read_b128 v[222:225], v95 offset:24576
	v_mov_b32_e32 v153, v152
	s_nop 1
	v_permlane32_swap_b32_e32 v153, v152
	v_max_f32_e32 v152, v152, v153
	v_add_f32_e32 v153, 0x41000000, v217
	v_cmp_lt_f32_e32 vcc, v153, v152
	s_cbranch_vccnz .Lam_c1u0_rare
.Lam_c1u0_back:
	v_sub_f32_e32 v32, v32, v217
	v_exp_f32_e32 v32, v32
	v_sub_f32_e32 v33, v33, v217
	v_exp_f32_e32 v33, v33
	v_mfma_f32_32x32x16_bf16 v[48:63], v[226:229], v[74:77], v[48:63]
	ds_read_b128 v[226:229], v97 offset:24576
	v_sub_f32_e32 v34, v34, v217
	v_exp_f32_e32 v34, v34
	v_sub_f32_e32 v35, v35, v217
	v_exp_f32_e32 v35, v35
	v_sub_f32_e32 v36, v36, v217
	v_exp_f32_e32 v36, v36
	v_sub_f32_e32 v37, v37, v217
	v_mfma_f32_32x32x16_bf16 v[48:63], v[230:233], v[78:81], v[48:63]
	ds_read_b128 v[230:233], v147 offset:24576
	v_exp_f32_e32 v37, v37
	v_sub_f32_e32 v38, v38, v217
	v_exp_f32_e32 v38, v38
	v_sub_f32_e32 v39, v39, v217
	v_exp_f32_e32 v39, v39
	v_add_f32_e32 v153, v32, v33
	v_add_f32_e32 v153, v153, v34
	s_waitcnt lgkmcnt(7)
	v_mfma_f32_32x32x16_bf16 v[48:63], v[234:237], v[82:85], v[48:63]
	ds_read_b128 v[234:237], v242 offset:16384
	v_add_f32_e32 v153, v153, v35
	v_add_f32_e32 v153, v153, v36
	v_add_f32_e32 v153, v153, v37
	v_add_f32_e32 v153, v153, v38
	v_add_f32_e32 v153, v153, v39
	v_cvt_pk_bf16_f32 v32, v32, v33
	v_cvt_pk_bf16_f32 v33, v34, v35
	s_waitcnt lgkmcnt(7)
	v_mfma_f32_32x32x16_bf16 v[48:63], v[238:241], v[86:89], v[48:63]
	ds_read_b128 v[238:241], v246 offset:16384
	v_cvt_pk_bf16_f32 v34, v36, v37
	v_cvt_pk_bf16_f32 v35, v38, v39
	s_nop 1
	s_waitcnt lgkmcnt(1)
	v_mfma_f32_32x32x16_bf16 v[0:15], v[234:237], v[32:35], v[0:15]
	ds_read_b128 v[234:237], v200 offset:24576
	v_sub_f32_e32 v40, v40, v217
	v_exp_f32_e32 v40, v40
	v_sub_f32_e32 v41, v41, v217
	v_exp_f32_e32 v41, v41
	v_sub_f32_e32 v42, v42, v217
	v_exp_f32_e32 v42, v42
	v_sub_f32_e32 v43, v43, v217
	v_exp_f32_e32 v43, v43
	s_waitcnt lgkmcnt(1)
	v_mfma_f32_32x32x16_bf16 v[16:31], v[238:241], v[32:35], v[16:31]
	ds_read_b128 v[238:241], v201 offset:24576
	v_sub_f32_e32 v44, v44, v217
	v_exp_f32_e32 v44, v44
	v_sub_f32_e32 v45, v45, v217
	v_exp_f32_e32 v45, v45
	v_sub_f32_e32 v46, v46, v217
	v_exp_f32_e32 v46, v46
	v_sub_f32_e32 v47, v47, v217
	v_exp_f32_e32 v47, v47
	v_add_f32_e32 v153, v153, v40
	v_add_f32_e32 v153, v153, v41
	v_add_f32_e32 v153, v153, v42
	v_add_f32_e32 v153, v153, v43
	v_add_f32_e32 v153, v153, v44
	v_add_f32_e32 v153, v153, v45
	v_add_f32_e32 v153, v153, v46
	v_add_f32_e32 v153, v153, v47
	v_cvt_pk_bf16_f32 v40, v40, v41
	v_cvt_pk_bf16_f32 v41, v42, v43
	v_cvt_pk_bf16_f32 v42, v44, v45
	v_cvt_pk_bf16_f32 v43, v46, v47
	v_add_f32_e32 v96, v96, v153
	s_nop 0
	v_mfma_f32_32x32x16_bf16 v[0:15], v[90:93], v[40:43], v[0:15]
	v_mfma_f32_32x32x16_bf16 v[16:31], v[148:151], v[40:43], v[16:31]
	ds_read_b128 v[90:93], v245 offset:16384
	ds_read_b128 v[148:151], v249 offset:16384
	v_mfma_f32_32x32x16_bf16 v[32:47], v[218:221], v[66:69], 0
	ds_read_b128 v[218:221], v94 offset:32768
	v_max3_f32 v152, v48, v49, v50
	v_max3_f32 v152, v152, v51, v52
	v_max3_f32 v152, v152, v53, v54
	v_max3_f32 v152, v152, v55, v56
	v_max3_f32 v152, v152, v57, v58
	v_max3_f32 v152, v152, v59, v60
	v_max3_f32 v152, v152, v61, v62
	v_max_f32_e32 v152, v152, v63
	v_mfma_f32_32x32x16_bf16 v[32:47], v[222:225], v[70:73], v[32:47]
	ds_read_b128 v[222:225], v95 offset:32768
	v_mov_b32_e32 v153, v152
	s_nop 1
	v_permlane32_swap_b32_e32 v153, v152
	v_max_f32_e32 v152, v152, v153
	v_add_f32_e32 v153, 0x41000000, v217
	v_cmp_lt_f32_e32 vcc, v153, v152
	s_cbranch_vccnz .Lam_c1u1_rare

.Lam_c1u3_back:
	v_sub_f32_e32 v48, v48, v217
	v_exp_f32_e32 v48, v48
	v_sub_f32_e32 v49, v49, v217
	v_exp_f32_e32 v49, v49
	v_mfma_f32_32x32x16_bf16 v[32:47], v[226:229], v[74:77], v[32:47]
	ds_read_b128 v[226:229], v97 offset:8192
	v_sub_f32_e32 v50, v50, v217
	v_exp_f32_e32 v50, v50
	v_sub_f32_e32 v51, v51, v217
	v_exp_f32_e32 v51, v51
	v_sub_f32_e32 v52, v52, v217
	v_exp_f32_e32 v52, v52
	v_sub_f32_e32 v53, v53, v217
	v_mfma_f32_32x32x16_bf16 v[32:47], v[230:233], v[78:81], v[32:47]
	ds_read_b128 v[230:233], v147 offset:8192
	v_exp_f32_e32 v53, v53
	v_sub_f32_e32 v54, v54, v217
	v_exp_f32_e32 v54, v54
	v_sub_f32_e32 v55, v55, v217
	v_exp_f32_e32 v55, v55
	v_add_f32_e32 v153, v48, v49
	v_add_f32_e32 v153, v153, v50
	s_waitcnt lgkmcnt(7)
	v_mfma_f32_32x32x16_bf16 v[32:47], v[234:237], v[82:85], v[32:47]
	ds_read_b128 v[234:237], v244 offset:40960
	v_add_f32_e32 v153, v153, v51
	v_add_f32_e32 v153, v153, v52
	v_add_f32_e32 v153, v153, v53
	v_add_f32_e32 v153, v153, v54
	v_add_f32_e32 v153, v153, v55
	v_cvt_pk_bf16_f32 v48, v48, v49
	v_cvt_pk_bf16_f32 v49, v50, v51
	s_waitcnt lgkmcnt(7)
	v_mfma_f32_32x32x16_bf16 v[32:47], v[238:241], v[86:89], v[32:47]
	ds_read_b128 v[238:241], v248 offset:40960
	v_cvt_pk_bf16_f32 v50, v52, v53
	v_cvt_pk_bf16_f32 v51, v54, v55
	s_nop 1
	s_waitcnt lgkmcnt(1)
	v_mfma_f32_32x32x16_bf16 v[0:15], v[234:237], v[48:51], v[0:15]
	ds_read_b128 v[234:237], v200 offset:8192
	v_sub_f32_e32 v56, v56, v217
	v_exp_f32_e32 v56, v56
	v_sub_f32_e32 v57, v57, v217
	v_exp_f32_e32 v57, v57
	v_sub_f32_e32 v58, v58, v217
	v_exp_f32_e32 v58, v58
	v_sub_f32_e32 v59, v59, v217
	v_exp_f32_e32 v59, v59
	s_waitcnt lgkmcnt(1)
	v_mfma_f32_32x32x16_bf16 v[16:31], v[238:241], v[48:51], v[16:31]
	ds_read_b128 v[238:241], v201 offset:8192
	v_sub_f32_e32 v60, v60, v217
	v_exp_f32_e32 v60, v60
	v_sub_f32_e32 v61, v61, v217
	v_exp_f32_e32 v61, v61
	v_sub_f32_e32 v62, v62, v217
	v_exp_f32_e32 v62, v62
	v_sub_f32_e32 v63, v63, v217
	v_exp_f32_e32 v63, v63
	v_add_f32_e32 v153, v153, v56
	v_add_f32_e32 v153, v153, v57
	v_add_f32_e32 v153, v153, v58
	v_add_f32_e32 v153, v153, v59
	v_add_f32_e32 v153, v153, v60
	v_add_f32_e32 v153, v153, v61
	v_add_f32_e32 v153, v153, v62
	v_add_f32_e32 v153, v153, v63
	v_cvt_pk_bf16_f32 v56, v56, v57
	v_cvt_pk_bf16_f32 v57, v58, v59
	v_cvt_pk_bf16_f32 v58, v60, v61
	v_cvt_pk_bf16_f32 v59, v62, v63
	v_add_f32_e32 v96, v96, v153
	s_nop 0
	v_mfma_f32_32x32x16_bf16 v[0:15], v[90:93], v[56:59], v[0:15]
	v_mfma_f32_32x32x16_bf16 v[16:31], v[148:151], v[56:59], v[16:31]
	s_add_i32 s81, s81, -1
	s_cmp_eq_u32 s81, 0
	s_cbranch_scc1 .Lam_exit
	s_waitcnt vmcnt(3)
	s_barrier
	s_add_u32 m0, s82, 0xc000
	v_lshl_add_u64 v[152:153], v[142:143], 0, s[84:85]
	global_load_lds_dwordx4 v[152:153], off
	s_add_u32 m0, s82, 0xc400
	v_lshl_add_u64 v[152:153], v[144:145], 0, s[84:85]
	global_load_lds_dwordx4 v[152:153], off
	s_add_u32 m0, s83, 0x10000
	v_lshl_add_u64 v[152:153], v[140:141], 0, s[86:87]
	global_load_lds_dwordx4 v[152:153], off
	s_add_u32 m0, s82, 0x12000
	v_lshl_add_u64 v[152:153], v[142:143], 0, s[88:89]
	global_load_lds_dwordx4 v[152:153], off
	s_add_u32 m0, s82, 0x12400
	v_lshl_add_u64 v[152:153], v[144:145], 0, s[88:89]
	global_load_lds_dwordx4 v[152:153], off
	s_add_u32 m0, s83, 0x16000
	v_lshl_add_u64 v[152:153], v[140:141], 0, s[90:91]
	global_load_lds_dwordx4 v[152:153], off
	s_add_u32 s84, s84, 0x30000
	s_addc_u32 s85, s85, 0
	s_add_u32 s88, s88, 0x30000
	s_addc_u32 s89, s89, 0
	s_add_u32 s86, s86, 0x100
	s_addc_u32 s87, s87, 0
	s_add_u32 s90, s90, 0x100
	s_addc_u32 s91, s91, 0
	v_add_u32_e32 v242, 0xc000, v242
	v_add_u32_e32 v243, 0xc000, v243
	v_add_u32_e32 v244, 0xc000, v244
	v_add_u32_e32 v245, 0xc000, v245
	v_add_u32_e32 v246, 0xc000, v246
	v_add_u32_e32 v247, 0xc000, v247
	v_add_u32_e32 v248, 0xc000, v248
	v_add_u32_e32 v249, 0xc000, v249
	ds_read_b128 v[90:93], v243 offset:16384
	ds_read_b128 v[148:151], v247 offset:16384
	v_mfma_f32_32x32x16_bf16 v[48:63], v[218:221], v[66:69], 0
	ds_read_b128 v[218:221], v94 offset:24576
	v_max3_f32 v152, v32, v33, v34
	v_max3_f32 v152, v152, v35, v36
	v_max3_f32 v152, v152, v37, v38
	v_max3_f32 v152, v152, v39, v40
	v_max3_f32 v152, v152, v41, v42
	v_max3_f32 v152, v152, v43, v44
	v_max3_f32 v152, v152, v45, v46
	v_max_f32_e32 v152, v152, v47
	v_mfma_f32_32x32x16_bf16 v[48:63], v[222:225], v[70:73], v[48:63]
	ds_read_b128 v[222:225], v95 offset:24576
	v_mov_b32_e32 v153, v152
	s_nop 1
	v_permlane32_swap_b32_e32 v153, v152
	v_max_f32_e32 v152, v152, v153
	v_add_f32_e32 v153, 0x41000000, v217
	v_cmp_lt_f32_e32 vcc, v153, v152
	s_cbranch_vccnz .Lam_c2u0_rare

.Lam_c2u1_back:
	v_sub_f32_e32 v48, v48, v217
	v_exp_f32_e32 v48, v48
	v_sub_f32_e32 v49, v49, v217
	v_exp_f32_e32 v49, v49
	v_mfma_f32_32x32x16_bf16 v[32:47], v[226:229], v[74:77], v[32:47]
	ds_read_b128 v[226:229], v97 offset:32768
	v_sub_f32_e32 v50, v50, v217
	v_exp_f32_e32 v50, v50
	v_sub_f32_e32 v51, v51, v217
	v_exp_f32_e32 v51, v51
	v_sub_f32_e32 v52, v52, v217
	v_exp_f32_e32 v52, v52
	v_sub_f32_e32 v53, v53, v217
	v_mfma_f32_32x32x16_bf16 v[32:47], v[230:233], v[78:81], v[32:47]
	ds_read_b128 v[230:233], v147 offset:32768
	v_exp_f32_e32 v53, v53
	v_sub_f32_e32 v54, v54, v217
	v_exp_f32_e32 v54, v54
	v_sub_f32_e32 v55, v55, v217
	v_exp_f32_e32 v55, v55
	v_add_f32_e32 v153, v48, v49
	v_add_f32_e32 v153, v153, v50
	s_waitcnt lgkmcnt(7)
	v_mfma_f32_32x32x16_bf16 v[32:47], v[234:237], v[82:85], v[32:47]
	ds_read_b128 v[234:237], v244 offset:16384
	v_add_f32_e32 v153, v153, v51
	v_add_f32_e32 v153, v153, v52
	v_add_f32_e32 v153, v153, v53
	v_add_f32_e32 v153, v153, v54
	v_add_f32_e32 v153, v153, v55
	v_cvt_pk_bf16_f32 v48, v48, v49
	v_cvt_pk_bf16_f32 v49, v50, v51
	s_waitcnt lgkmcnt(7)
	v_mfma_f32_32x32x16_bf16 v[32:47], v[238:241], v[86:89], v[32:47]
	ds_read_b128 v[238:241], v248 offset:16384
	v_cvt_pk_bf16_f32 v50, v52, v53
	v_cvt_pk_bf16_f32 v51, v54, v55
	s_nop 1
	s_waitcnt lgkmcnt(1)
	v_mfma_f32_32x32x16_bf16 v[0:15], v[234:237], v[48:51], v[0:15]
	ds_read_b128 v[234:237], v200 offset:32768
	v_sub_f32_e32 v56, v56, v217
	v_exp_f32_e32 v56, v56
	v_sub_f32_e32 v57, v57, v217
	v_exp_f32_e32 v57, v57
	v_sub_f32_e32 v58, v58, v217
	v_exp_f32_e32 v58, v58
	v_sub_f32_e32 v59, v59, v217
	v_exp_f32_e32 v59, v59
	s_waitcnt lgkmcnt(1)
	v_mfma_f32_32x32x16_bf16 v[16:31], v[238:241], v[48:51], v[16:31]
	ds_read_b128 v[238:241], v201 offset:32768
	v_sub_f32_e32 v60, v60, v217
	v_exp_f32_e32 v60, v60
	v_sub_f32_e32 v61, v61, v217
	v_exp_f32_e32 v61, v61
	v_sub_f32_e32 v62, v62, v217
	v_exp_f32_e32 v62, v62
	v_sub_f32_e32 v63, v63, v217
	v_exp_f32_e32 v63, v63
	v_add_f32_e32 v153, v153, v56
	v_add_f32_e32 v153, v153, v57
	v_add_f32_e32 v153, v153, v58
	v_add_f32_e32 v153, v153, v59
	v_add_f32_e32 v153, v153, v60
	v_add_f32_e32 v153, v153, v61
	v_add_f32_e32 v153, v153, v62
	v_add_f32_e32 v153, v153, v63
	v_cvt_pk_bf16_f32 v56, v56, v57
	v_cvt_pk_bf16_f32 v57, v58, v59
	v_cvt_pk_bf16_f32 v58, v60, v61
	v_cvt_pk_bf16_f32 v59, v62, v63
	v_add_f32_e32 v96, v96, v153
	s_nop 0
	v_mfma_f32_32x32x16_bf16 v[0:15], v[90:93], v[56:59], v[0:15]
	v_mfma_f32_32x32x16_bf16 v[16:31], v[148:151], v[56:59], v[16:31]
	v_add_u32_e32 v94, 0xfffe8000, v94
	v_add_u32_e32 v95, 0xfffe8000, v95
	v_add_u32_e32 v97, 0xfffe8000, v97
	v_add_u32_e32 v147, 0xfffe8000, v147
	v_add_u32_e32 v200, 0xfffe8000, v200
	v_add_u32_e32 v201, 0xfffe8000, v201
	ds_read_b128 v[90:93], v243 offset:40960
	ds_read_b128 v[148:151], v247 offset:40960
	v_mfma_f32_32x32x16_bf16 v[48:63], v[218:221], v[66:69], 0
	ds_read_b128 v[218:221], v94
	v_max3_f32 v152, v32, v33, v34
	v_max3_f32 v152, v152, v35, v36
	v_max3_f32 v152, v152, v37, v38
	v_max3_f32 v152, v152, v39, v40
	v_max3_f32 v152, v152, v41, v42
	v_max3_f32 v152, v152, v43, v44
	v_max3_f32 v152, v152, v45, v46
	v_max_f32_e32 v152, v152, v47
	v_mfma_f32_32x32x16_bf16 v[48:63], v[222:225], v[70:73], v[48:63]
	ds_read_b128 v[222:225], v95
	v_mov_b32_e32 v153, v152
	s_nop 1
	v_permlane32_swap_b32_e32 v153, v152
	v_max_f32_e32 v152, v152, v153
	v_add_f32_e32 v153, 0x41000000, v217
	v_cmp_lt_f32_e32 vcc, v153, v152
	s_cbranch_vccnz .Lam_c2u2_rare

.Lam_c2u3_back:
	v_sub_f32_e32 v48, v48, v217
	v_exp_f32_e32 v48, v48
	v_sub_f32_e32 v49, v49, v217
	v_exp_f32_e32 v49, v49
	v_mfma_f32_32x32x16_bf16 v[32:47], v[226:229], v[74:77], v[32:47]
	ds_read_b128 v[226:229], v97 offset:8192
	v_sub_f32_e32 v50, v50, v217
	v_exp_f32_e32 v50, v50
	v_sub_f32_e32 v51, v51, v217
	v_exp_f32_e32 v51, v51
	v_sub_f32_e32 v52, v52, v217
	v_exp_f32_e32 v52, v52
	v_sub_f32_e32 v53, v53, v217
	v_mfma_f32_32x32x16_bf16 v[32:47], v[230:233], v[78:81], v[32:47]
	ds_read_b128 v[230:233], v147 offset:8192
	v_exp_f32_e32 v53, v53
	v_sub_f32_e32 v54, v54, v217
	v_exp_f32_e32 v54, v54
	v_sub_f32_e32 v55, v55, v217
	v_exp_f32_e32 v55, v55
	v_add_f32_e32 v153, v48, v49
	v_add_f32_e32 v153, v153, v50
	s_waitcnt lgkmcnt(7)
	v_mfma_f32_32x32x16_bf16 v[32:47], v[234:237], v[82:85], v[32:47]
	ds_read_b128 v[234:237], v244 offset:40960
	v_add_f32_e32 v153, v153, v51
	v_add_f32_e32 v153, v153, v52
	v_add_f32_e32 v153, v153, v53
	v_add_f32_e32 v153, v153, v54
	v_add_f32_e32 v153, v153, v55
	v_cvt_pk_bf16_f32 v48, v48, v49
	v_cvt_pk_bf16_f32 v49, v50, v51
	s_waitcnt lgkmcnt(7)
	v_mfma_f32_32x32x16_bf16 v[32:47], v[238:241], v[86:89], v[32:47]
	ds_read_b128 v[238:241], v248 offset:40960
	v_cvt_pk_bf16_f32 v50, v52, v53
	v_cvt_pk_bf16_f32 v51, v54, v55
	s_nop 1
	s_waitcnt lgkmcnt(1)
	v_mfma_f32_32x32x16_bf16 v[0:15], v[234:237], v[48:51], v[0:15]
	ds_read_b128 v[234:237], v200 offset:8192
	v_sub_f32_e32 v56, v56, v217
	v_exp_f32_e32 v56, v56
	v_sub_f32_e32 v57, v57, v217
	v_exp_f32_e32 v57, v57
	v_sub_f32_e32 v58, v58, v217
	v_exp_f32_e32 v58, v58
	v_sub_f32_e32 v59, v59, v217
	v_exp_f32_e32 v59, v59
	s_waitcnt lgkmcnt(1)
	v_mfma_f32_32x32x16_bf16 v[16:31], v[238:241], v[48:51], v[16:31]
	ds_read_b128 v[238:241], v201 offset:8192
	v_sub_f32_e32 v60, v60, v217
	v_exp_f32_e32 v60, v60
	v_sub_f32_e32 v61, v61, v217
	v_exp_f32_e32 v61, v61
	v_sub_f32_e32 v62, v62, v217
	v_exp_f32_e32 v62, v62
	v_sub_f32_e32 v63, v63, v217
	v_exp_f32_e32 v63, v63
	v_add_f32_e32 v153, v153, v56
	v_add_f32_e32 v153, v153, v57
	v_add_f32_e32 v153, v153, v58
	v_add_f32_e32 v153, v153, v59
	v_add_f32_e32 v153, v153, v60
	v_add_f32_e32 v153, v153, v61
	v_add_f32_e32 v153, v153, v62
	v_add_f32_e32 v153, v153, v63
	v_cvt_pk_bf16_f32 v56, v56, v57
	v_cvt_pk_bf16_f32 v57, v58, v59
	v_cvt_pk_bf16_f32 v58, v60, v61
	v_cvt_pk_bf16_f32 v59, v62, v63
	v_add_f32_e32 v96, v96, v153
	s_nop 0
	v_mfma_f32_32x32x16_bf16 v[0:15], v[90:93], v[56:59], v[0:15]
	v_mfma_f32_32x32x16_bf16 v[16:31], v[148:151], v[56:59], v[16:31]
	s_add_i32 s81, s81, -1
	s_cmp_eq_u32 s81, 0
	s_cbranch_scc0 .Lam_loop
.Lam_exit:
	s_waitcnt lgkmcnt(0)
	s_branch .LBB0_181
.Lam_c0u0_rare:
	s_nop 0
	v_cndmask_b32_e32 v153, v217, v152, vcc
	v_sub_f32_e32 v152, v217, v153
	v_exp_f32_e32 v152, v152
	v_mov_b32_e32 v217, v153
	v_mul_f32_e32 v96, v96, v152
	v_pk_mul_f32 v[0:1], v[0:1], v[152:153] op_sel_hi:[1,0]
	v_pk_mul_f32 v[2:3], v[2:3], v[152:153] op_sel_hi:[1,0]
	v_pk_mul_f32 v[4:5], v[4:5], v[152:153] op_sel_hi:[1,0]
	v_pk_mul_f32 v[6:7], v[6:7], v[152:153] op_sel_hi:[1,0]
	v_pk_mul_f32 v[8:9], v[8:9], v[152:153] op_sel_hi:[1,0]
	v_pk_mul_f32 v[10:11], v[10:11], v[152:153] op_sel_hi:[1,0]
	v_pk_mul_f32 v[12:13], v[12:13], v[152:153] op_sel_hi:[1,0]
	v_pk_mul_f32 v[14:15], v[14:15], v[152:153] op_sel_hi:[1,0]
	v_pk_mul_f32 v[16:17], v[16:17], v[152:153] op_sel_hi:[1,0]
	v_pk_mul_f32 v[18:19], v[18:19], v[152:153] op_sel_hi:[1,0]
	v_pk_mul_f32 v[20:21], v[20:21], v[152:153] op_sel_hi:[1,0]
	v_pk_mul_f32 v[22:23], v[22:23], v[152:153] op_sel_hi:[1,0]
	v_pk_mul_f32 v[24:25], v[24:25], v[152:153] op_sel_hi:[1,0]
	v_pk_mul_f32 v[26:27], v[26:27], v[152:153] op_sel_hi:[1,0]
	v_pk_mul_f32 v[28:29], v[28:29], v[152:153] op_sel_hi:[1,0]
	v_pk_mul_f32 v[30:31], v[30:31], v[152:153] op_sel_hi:[1,0]
	s_branch .Lam_c0u0_back

.Lam_islands_end:
.LBB0_180:
	s_mov_b32 s81, s80
	s_mov_b32 s82, s80
	s_mov_b32 s83, s80
	s_mov_b32 s84, s80
	s_mov_b32 s85, s80
	s_mov_b32 s86, s80
	s_mov_b32 s87, s80
	s_mov_b32 s88, s80
	s_mov_b32 s89, s80
	s_mov_b32 s90, s80
	s_mov_b32 s91, s80
	s_mov_b32 s92, s80
	s_mov_b32 s93, s80
	s_mov_b32 s94, s80
	s_mov_b32 s95, s80
	v_mov_b64_e32 v[0:1], s[80:81]
	v_mov_b64_e32 v[14:15], s[94:95]
	v_mov_b64_e32 v[2:3], s[82:83]
	v_mov_b64_e32 v[4:5], s[84:85]
	v_mov_b64_e32 v[6:7], s[86:87]
	v_mov_b64_e32 v[8:9], s[88:89]
	v_mov_b64_e32 v[10:11], s[90:91]
	v_mov_b64_e32 v[12:13], s[92:93]
	v_mov_b64_e32 v[30:31], v[14:15]
	v_mov_b64_e32 v[62:63], v[14:15]
	v_mov_b32_e32 v217, 0xf149f2ca
	v_mov_b32_e32 v96, 0
	v_mov_b64_e32 v[28:29], v[12:13]
	v_mov_b64_e32 v[26:27], v[10:11]
	v_mov_b64_e32 v[24:25], v[8:9]
	v_mov_b64_e32 v[22:23], v[6:7]
	v_mov_b64_e32 v[20:21], v[4:5]
	v_mov_b64_e32 v[18:19], v[2:3]
	v_mov_b64_e32 v[16:17], v[0:1]
	v_mov_b64_e32 v[60:61], v[12:13]
	v_mov_b64_e32 v[58:59], v[10:11]
	v_mov_b64_e32 v[56:57], v[8:9]
	v_mov_b64_e32 v[54:55], v[6:7]
	v_mov_b64_e32 v[52:53], v[4:5]
	v_mov_b64_e32 v[50:51], v[2:3]
	v_mov_b64_e32 v[48:49], v[0:1]
